# v040_attnprio
# speedup vs baseline: 1.0434x; 1.0045x over previous
; __device__ __forceinline__ void attn_wave_item(const Params& p, int witem, const int tidx) {
;     ...
;     u32x4 vf[8], kn[8];
;     {
;       const int tn = tile > 0 ? tile - 1 : 0;
;       const char* vp = vbase + (size_t)tile * 8192;
;       const char* kp = kbase + (size_t)tn * 8192;
; #pragma unroll
;       for (int i = 0; i < 8; ++i) vf[i] = *reinterpret_cast<const u32x4*>(vp + i * 1024);
; #pragma unroll
;       for (int ks = 0; ks < 8; ++ks) kn[ks] = *reinterpret_cast<const u32x4*>(kp + ks * 1024);
;     }
;     __builtin_amdgcn_sched_barrier(0);
;     f32x16 S, S2;
; #pragma unroll
;     for (int i = 0; i < 16; ++i) { S[i] = 0.f; S2[i] = 0.f; }
; #pragma unroll
;     for (int ks = 0; ks < 8; ks += 2) {
;       u32x4 qa = *reinterpret_cast<const u32x4*>(qlds + ks * 1024);
;       u32x4 qb = *reinterpret_cast<const u32x4*>(qlds + (ks + 1) * 1024);
;       S = __builtin_amdgcn_mfma_f32_32x32x16_bf16(as_bf16x8(kf[ks]), as_bf16x8(qa), S, 0, 0, 0);
;       S2 = __builtin_amdgcn_mfma_f32_32x32x16_bf16(as_bf16x8(kf[ks + 1]), as_bf16x8(qb), S2, 0, 0, 0);
;     }
; #pragma unroll
;     for (int i = 0; i < 16; ++i) S[i] += S2[i];
;     const bool diag = (tile == qt);
;     float be[16], om[16];
; #pragma unroll
;     for (int r = 0; r < 16; ++r) {
;       float z = S[r];
;       float e = __builtin_amdgcn_exp2f(-fabsf(z));
;       float rr = __builtin_amdgcn_rcpf(1.f + e);
;       float sm = e * rr;
;       int kl = (r & 3) + 8 * (r >> 2) + 4 * half;
;       bool v = !diag || (kl < n);
;       bool pos = z >= 0.f;
;       be[r] = v ? (pos ? rr : sm) : 0.f;
;       om[r] = v ? (pos ? sm : rr) : 1.f;
;     }
.LBB0_119:
	v_lshl_add_u64 v[68:69], v[174:175], 0, s[48:49]
	s_mov_b32 s42, 0x20900000
	v_add_co_u32_e64 v72, s[42:43], s42, v68
	v_sub_u32_e64 v162, v169, 1 clamp
	s_nop 0
	v_addc_co_u32_e64 v73, s[42:43], 0, v69, s[42:43]
	s_mov_b32 s42, 0x20901000
	s_nop 0
	v_add_co_u32_e64 v68, s[42:43], s42, v68
	v_lshlrev_b64 v[70:71], 13, v[162:163]
	s_nop 0
	v_addc_co_u32_e64 v69, s[42:43], 0, v69, s[42:43]
	global_load_dwordx4 v[154:157], v[72:73], off offset:1024
	global_load_dwordx4 v[150:153], v[72:73], off offset:2048
	global_load_dwordx4 v[142:145], v[72:73], off offset:3072
	global_load_dwordx4 v[158:161], v[68:69], off offset:-4096
	global_load_dwordx4 v[146:149], v[68:69], off
	global_load_dwordx4 v[138:141], v[68:69], off offset:1024
	global_load_dwordx4 v[134:137], v[68:69], off offset:2048
	global_load_dwordx4 v[130:133], v[68:69], off offset:3072
	s_waitcnt vmcnt(12)
	v_mov_b64_e32 v[198:199], v[112:113]
	v_mov_b64_e32 v[202:203], v[108:109]
	v_mov_b64_e32 v[80:81], v[102:103]
	v_mov_b64_e32 v[64:65], v[98:99]
	v_lshl_add_u64 v[68:69], v[170:171], 0, v[70:71]
	v_mov_b64_e32 v[196:197], v[110:111]
	v_mov_b64_e32 v[200:201], v[106:107]
	v_mov_b64_e32 v[82:83], v[104:105]
	v_mov_b64_e32 v[66:67], v[100:101]
	global_load_dwordx4 v[98:101], v[68:69], off
	global_load_dwordx4 v[102:105], v[68:69], off offset:1024
	global_load_dwordx4 v[106:109], v[68:69], off offset:2048
	global_load_dwordx4 v[110:113], v[68:69], off offset:3072
	v_add_co_u32_e64 v68, s[42:43], s58, v68
	s_waitcnt vmcnt(12)
	v_mov_b64_e32 v[182:183], v[128:129]
	v_mov_b64_e32 v[186:187], v[124:125]
	v_mov_b64_e32 v[190:191], v[120:121]
	v_mov_b64_e32 v[194:195], v[116:117]
	v_addc_co_u32_e64 v69, s[42:43], 0, v69, s[42:43]
	v_mov_b64_e32 v[180:181], v[126:127]
	v_mov_b64_e32 v[184:185], v[122:123]
	v_mov_b64_e32 v[188:189], v[118:119]
	v_mov_b64_e32 v[192:193], v[114:115]
	global_load_dwordx4 v[114:117], v[68:69], off
	global_load_dwordx4 v[118:121], v[68:69], off offset:1024
	global_load_dwordx4 v[122:125], v[68:69], off offset:2048
	global_load_dwordx4 v[126:129], v[68:69], off offset:3072
	ds_read_b128 v[68:71], v173
	ds_read_b128 v[84:87], v173 offset:1024
	ds_read_b128 v[204:207], v173 offset:2048
	ds_read_b128 v[222:225], v173 offset:3072
	s_cmp_lg_u32 s48, 0
	s_cselect_b64 s[50:51], -1, 0
	s_waitcnt lgkmcnt(3)
	s_setprio 1
	v_mfma_f32_32x32x16_bf16 v[64:79], v[64:67], v[68:71], 0
	s_or_b64 s[44:45], s[6:7], s[50:51]
	s_waitcnt lgkmcnt(2)
	v_mfma_f32_32x32x16_bf16 v[80:95], v[80:83], v[84:87], 0
	s_waitcnt lgkmcnt(1)
	v_mfma_f32_32x32x16_bf16 v[64:79], v[200:203], v[204:207], v[64:79]
	s_waitcnt lgkmcnt(0)
	v_mfma_f32_32x32x16_bf16 v[80:95], v[196:199], v[222:225], v[80:95]
	ds_read_b128 v[196:199], v173 offset:4096
	ds_read_b128 v[200:203], v173 offset:5120
	s_waitcnt lgkmcnt(1)
	v_mfma_f32_32x32x16_bf16 v[64:79], v[192:195], v[196:199], v[64:79]
	s_waitcnt lgkmcnt(0)
	v_mfma_f32_32x32x16_bf16 v[80:95], v[188:191], v[200:203], v[80:95]
	ds_read_b128 v[188:191], v173 offset:6144
	ds_read_b128 v[192:195], v173 offset:7168
	s_waitcnt lgkmcnt(1)
	v_mfma_f32_32x32x16_bf16 v[64:79], v[184:187], v[188:191], v[64:79]
	s_waitcnt lgkmcnt(0)
	v_mfma_f32_32x32x16_bf16 v[80:95], v[180:183], v[192:195], v[80:95]
	s_setprio 0
	s_nop 11
	v_add_f32_e32 v64, v64, v80
	v_exp_f32_e64 v80, -|v64|
	v_add_f32_e32 v65, v65, v81
	v_add_f32_e32 v66, v66, v82
	v_exp_f32_e64 v82, -|v65|
	v_add_f32_e32 v81, 1.0, v80
	v_rcp_f32_e32 v81, v81
	v_add_f32_e32 v67, v67, v83
	v_add_f32_e32 v83, 1.0, v82
	v_cmp_le_f32_e64 s[42:43], 0, v64
	v_mul_f32_e32 v80, v80, v81
	v_rcp_f32_e32 v83, v83
	v_cndmask_b32_e64 v64, v80, v81, s[42:43]
	v_add_f32_e32 v68, v68, v84
	v_cndmask_b32_e64 v84, 0, v64, s[44:45]
	v_cndmask_b32_e64 v64, v81, v80, s[42:43]
	v_exp_f32_e64 v81, -|v66|
	v_cndmask_b32_e64 v80, 1.0, v64, s[44:45]
	v_mul_f32_e32 v64, v82, v83
	v_cmp_le_f32_e64 s[42:43], 0, v65
	s_or_b64 s[44:45], s[8:9], s[50:51]
	v_add_f32_e32 v69, v69, v85
	v_cndmask_b32_e64 v65, v64, v83, s[42:43]
	v_cndmask_b32_e64 v64, v83, v64, s[42:43]
	v_cndmask_b32_e64 v82, 0, v65, s[44:45]
	v_add_f32_e32 v65, 1.0, v81
	v_cndmask_b32_e64 v83, 1.0, v64, s[44:45]
	v_exp_f32_e64 v64, -|v67|
	v_rcp_f32_e32 v65, v65
	v_cmp_le_f32_e64 s[42:43], 0, v66
	s_or_b64 s[44:45], s[10:11], s[50:51]
	v_add_f32_e32 v85, 1.0, v64
	v_mul_f32_e32 v81, v81, v65
	v_rcp_f32_e32 v85, v85
	v_cndmask_b32_e64 v66, v81, v65, s[42:43]
	v_cndmask_b32_e64 v65, v65, v81, s[42:43]
	v_cndmask_b32_e64 v81, 1.0, v65, s[44:45]
	v_exp_f32_e64 v65, -|v68|
	v_mul_f32_e32 v64, v64, v85
	v_cmp_le_f32_e64 s[42:43], 0, v67
	v_exp_f32_e64 v67, -|v69|
	v_add_f32_e32 v70, v70, v86
	v_cndmask_b32_e64 v86, 0, v66, s[44:45]
	v_cndmask_b32_e64 v66, v64, v85, s[42:43]
	s_or_b64 s[44:45], s[12:13], s[50:51]
	v_add_f32_e32 v71, v71, v87
	v_cndmask_b32_e64 v87, 0, v66, s[44:45]
	v_add_f32_e32 v66, 1.0, v65
	v_rcp_f32_e32 v66, v66
	v_cndmask_b32_e64 v64, v85, v64, s[42:43]
	v_cmp_le_f32_e64 s[42:43], 0, v68
	v_add_f32_e32 v68, 1.0, v67
	v_rcp_f32_e32 v68, v68
	v_cndmask_b32_e64 v85, 1.0, v64, s[44:45]
	v_mul_f32_e32 v64, v65, v66
	v_cndmask_b32_e64 v65, v64, v66, s[42:43]
	s_or_b64 s[44:45], s[14:15], s[50:51]
	v_add_f32_e32 v72, v72, v88
	v_cndmask_b32_e64 v88, 0, v65, s[44:45]
	v_mul_f32_e32 v65, v67, v68
	v_exp_f32_e64 v67, -|v70|
	v_cndmask_b32_e64 v64, v66, v64, s[42:43]
	v_cmp_le_f32_e64 s[42:43], 0, v69
	v_cndmask_b32_e64 v64, 1.0, v64, s[44:45]
	s_or_b64 s[44:45], s[16:17], s[50:51]
	v_cndmask_b32_e64 v66, v65, v68, s[42:43]
	v_add_f32_e32 v73, v73, v89
	v_cndmask_b32_e64 v89, 0, v66, s[44:45]
	v_add_f32_e32 v66, 1.0, v67
	v_cndmask_b32_e64 v65, v68, v65, s[42:43]
; __device__ __forceinline__ void attn_wave_item(const Params& p, int witem, const int tidx) {
;     ...
;     for (int r = 0; r < 16; ++r) {
;       float z = S[r];
;       float e = __builtin_amdgcn_exp2f(-fabsf(z));
;       float rr = __builtin_amdgcn_rcpf(1.f + e);
;       float sm = e * rr;
;       int kl = (r & 3) + 8 * (r >> 2) + 4 * half;
;       bool v = !diag || (kl < n);
;       bool pos = z >= 0.f;
;       be[r] = v ? (pos ? rr : sm) : 0.f;
;       om[r] = v ? (pos ? sm : rr) : 1.f;
;     }
;     float gp[4], pgp[4];
; #pragma unroll
;     for (int gi = 0; gi < 4; ++gi) {
;       gp[gi] = (om[4 * gi] * om[4 * gi + 1]) * (om[4 * gi + 2] * om[4 * gi + 3]);
;       pgp[gi] = __shfl_xor(gp[gi], 32, 64);
;     }
;     float w[16];
;     float run = R;
; #pragma unroll
;     ...
;       float a = (half == 0) ? (run * pgp[gi]) : run;
; #pragma unroll
;       for (int r = 3; r >= 0; --r) {
;         int ri = 4 * gi + r;
;         w[ri] = be[ri] * a;
;         a *= om[ri];
;       }
;       run *= gp[gi] * pgp[gi];
;     }
;     R = run;
;     __builtin_amdgcn_sched_barrier(0);
;     bf16x8 pf[2];
; #pragma unroll
;     for (int m = 0; m < 2; ++m) {
;       u32x4 t;
;       t.x = pack2(w[8 * m + 0], w[8 * m + 1]);
;       t.y = pack2(w[8 * m + 2], w[8 * m + 3]);
;       t.z = pack2(w[8 * m + 4], w[8 * m + 5]);
;       t.w = pack2(w[8 * m + 6], w[8 * m + 7]);
;       pf[m] = as_bf16x8(t);
;     }
; #pragma unroll
;     for (int dt = 0; dt < 4; ++dt)
; #pragma unroll
;       for (int m = 0; m < 2; ++m) O[dt] = __builtin_amdgcn_mfma_f32_32x32x16_bf16(as_bf16x8(vf[dt * 2 + m]), pf[m], O[dt], 0, 0, 0);
;     if (__all(R < 1.17549435e-38f)) break;
	v_rcp_f32_e32 v69, v66
	v_cndmask_b32_e64 v66, 1.0, v65, s[44:45]
	v_exp_f32_e64 v65, -|v71|
	v_cmp_le_f32_e64 s[42:43], 0, v70
	v_mul_f32_e32 v67, v67, v69
	s_or_b64 s[44:45], s[18:19], s[50:51]
	v_add_f32_e32 v70, 1.0, v65
	v_rcp_f32_e32 v70, v70
	v_cndmask_b32_e64 v68, v67, v69, s[42:43]
	v_cndmask_b32_e64 v67, v69, v67, s[42:43]
	v_cndmask_b32_e64 v176, 1.0, v67, s[44:45]
	v_exp_f32_e64 v67, -|v72|
	v_mul_f32_e32 v65, v65, v70
	v_cmp_le_f32_e64 s[42:43], 0, v71
	v_add_f32_e32 v74, v74, v90
	v_cndmask_b32_e64 v90, 0, v68, s[44:45]
	v_cndmask_b32_e64 v68, v65, v70, s[42:43]
	s_or_b64 s[44:45], s[20:21], s[50:51]
	v_cndmask_b32_e64 v71, 0, v68, s[44:45]
	v_add_f32_e32 v68, 1.0, v67
	v_cndmask_b32_e64 v65, v70, v65, s[42:43]
	v_rcp_f32_e32 v69, v68
	v_cndmask_b32_e64 v68, 1.0, v65, s[44:45]
	v_exp_f32_e64 v65, -|v73|
	v_cmp_le_f32_e64 s[42:43], 0, v72
	v_mul_f32_e32 v67, v67, v69
	s_or_b64 s[44:45], s[22:23], s[50:51]
	v_add_f32_e32 v72, 1.0, v65
	v_rcp_f32_e32 v72, v72
	v_cndmask_b32_e64 v70, v67, v69, s[42:43]
	v_cndmask_b32_e64 v67, v69, v67, s[42:43]
	v_cmp_le_f32_e64 s[42:43], 0, v73
	v_mul_f32_e32 v65, v65, v72
	v_add_f32_e32 v75, v75, v91
	v_cndmask_b32_e64 v91, 0, v70, s[44:45]
	v_cndmask_b32_e64 v67, 1.0, v67, s[44:45]
	v_exp_f32_e64 v69, -|v74|
	v_cndmask_b32_e64 v70, v65, v72, s[42:43]
	s_or_b64 s[44:45], s[24:25], s[50:51]
	v_cndmask_b32_e64 v65, v72, v65, s[42:43]
	v_add_f32_e32 v77, v77, v93
	v_cndmask_b32_e64 v93, 1.0, v65, s[44:45]
	v_exp_f32_e64 v65, -|v75|
	v_add_f32_e32 v76, v76, v92
	v_cndmask_b32_e64 v92, 0, v70, s[44:45]
	v_add_f32_e32 v70, 1.0, v69
	v_rcp_f32_e32 v70, v70
	v_add_f32_e32 v73, 1.0, v65
	v_rcp_f32_e32 v73, v73
	v_cmp_le_f32_e64 s[42:43], 0, v74
	v_mul_f32_e32 v69, v69, v70
	s_or_b64 s[44:45], s[26:27], s[50:51]
	v_cndmask_b32_e64 v72, v69, v70, s[42:43]
	v_cndmask_b32_e64 v69, v70, v69, s[42:43]
	v_mul_f32_e32 v65, v65, v73
	v_cmp_le_f32_e64 s[42:43], 0, v75
	v_add_f32_e32 v78, v78, v94
	v_add_f32_e32 v79, v79, v95
	v_cndmask_b32_e64 v94, 0, v72, s[44:45]
	v_cndmask_b32_e64 v95, 1.0, v69, s[44:45]
	v_exp_f32_e64 v69, -|v76|
	v_cndmask_b32_e64 v70, v65, v73, s[42:43]
	s_or_b64 s[44:45], s[28:29], s[50:51]
	v_cndmask_b32_e64 v65, v73, v65, s[42:43]
	v_cndmask_b32_e64 v179, 1.0, v65, s[44:45]
	v_exp_f32_e64 v65, -|v77|
	v_cndmask_b32_e64 v162, 0, v70, s[44:45]
	v_add_f32_e32 v70, 1.0, v69
	v_rcp_f32_e32 v70, v70
	v_add_f32_e32 v73, 1.0, v65
	v_rcp_f32_e32 v73, v73
	v_cmp_le_f32_e64 s[42:43], 0, v76
	v_mul_f32_e32 v69, v69, v70
	s_or_b64 s[44:45], s[30:31], s[50:51]
	v_cndmask_b32_e64 v72, v69, v70, s[42:43]
	v_cndmask_b32_e64 v69, v70, v69, s[42:43]
	v_mul_f32_e32 v65, v65, v73
	v_cmp_le_f32_e64 s[42:43], 0, v77
	v_cndmask_b32_e64 v74, 0, v72, s[44:45]
	v_cndmask_b32_e64 v69, 1.0, v69, s[44:45]
	v_exp_f32_e64 v70, -|v78|
	v_cndmask_b32_e64 v72, v65, v73, s[42:43]
	s_or_b64 s[44:45], s[34:35], s[50:51]
	v_cndmask_b32_e64 v65, v73, v65, s[42:43]
	v_cndmask_b32_e64 v73, 1.0, v65, s[44:45]
	v_exp_f32_e64 v65, -|v79|
	v_cndmask_b32_e64 v75, 0, v72, s[44:45]
	v_add_f32_e32 v72, 1.0, v70
	v_rcp_f32_e32 v72, v72
	v_add_f32_e32 v77, 1.0, v65
	v_rcp_f32_e32 v77, v77
	v_cmp_le_f32_e64 s[42:43], 0, v78
	v_mul_f32_e32 v70, v70, v72
	s_or_b64 s[44:45], s[36:37], s[50:51]
	v_cndmask_b32_e64 v76, v70, v72, s[42:43]
	v_cndmask_b32_e64 v70, v72, v70, s[42:43]
	v_mul_f32_e32 v65, v65, v77
	v_cmp_le_f32_e64 s[42:43], 0, v79
	v_cndmask_b32_e64 v76, 0, v76, s[44:45]
	v_cndmask_b32_e64 v78, 1.0, v70, s[44:45]
	v_cndmask_b32_e64 v70, v65, v77, s[42:43]
	s_or_b64 s[44:45], s[38:39], s[50:51]
	v_cndmask_b32_e64 v65, v77, v65, s[42:43]
	v_cndmask_b32_e64 v77, 1.0, v65, s[44:45]
	v_mul_f32_e32 v65, v69, v73
	v_mul_f32_e32 v69, v78, v77
	v_mul_f32_e32 v69, v65, v69
	v_cndmask_b32_e64 v79, 0, v70, s[44:45]
	v_mul_f32_e32 v70, v80, v83
	ds_bpermute_b32 v80, v178, v69
	v_mul_f32_e32 v65, v67, v93
	v_mul_f32_e32 v67, v95, v179
	v_mul_f32_e32 v65, v65, v67
	ds_bpermute_b32 v67, v178, v65
	s_waitcnt lgkmcnt(1)
	v_mul_f32_e32 v180, v177, v80
	v_cndmask_b32_e32 v180, v177, v180, vcc
	v_mul_f32_e32 v77, v180, v77
	v_mul_f32_e32 v76, v76, v77
	v_mul_f32_e32 v77, v78, v77
	v_mul_f32_e32 v73, v73, v77
	v_mul_f32_e32 v69, v69, v80
	v_mul_f32_e32 v78, v75, v77
	v_mul_f32_e32 v77, v74, v73
	v_pk_mul_f32 v[74:75], v[176:177], v[68:69]
	s_waitcnt lgkmcnt(0)
	v_pk_mul_f32 v[64:65], v[64:65], v[66:67]
	v_mul_f32_e32 v67, v75, v67
	v_pk_mul_f32 v[64:65], v[64:65], v[74:75]
	ds_bpermute_b32 v73, v178, v64
	v_cndmask_b32_e32 v67, v75, v67, vcc
	v_mul_f32_e32 v74, v162, v67
	v_mul_f32_e32 v67, v179, v67
	v_mul_f32_e32 v75, v94, v67
	v_mul_f32_e32 v67, v95, v67
	v_mul_f32_e32 v80, v92, v67
	v_mul_f32_e32 v67, v93, v67
	v_mul_f32_e32 v91, v91, v67
	s_waitcnt lgkmcnt(0)
	v_mul_f32_e32 v67, v65, v73
	v_cndmask_b32_e32 v67, v65, v67, vcc
	v_mul_f32_e32 v72, v81, v85
	v_mul_f32_e32 v92, v71, v67
	v_mov_b32_e32 v71, v64
	v_mul_f32_e32 v67, v68, v67
	v_pk_mul_f32 v[68:69], v[70:71], v[72:73]
	ds_bpermute_b32 v64, v178, v68
	v_mul_f32_e32 v90, v90, v67
	v_mul_f32_e32 v67, v176, v67
	v_mul_f32_e32 v70, v89, v67
	v_mul_f32_e32 v66, v66, v67
	s_waitcnt lgkmcnt(0)
	v_pk_mul_f32 v[72:73], v[68:69], v[64:65]
	v_mul_f32_e32 v79, v180, v79
	v_mul_f32_e32 v64, v73, v64
	v_cndmask_b32_e32 v64, v73, v64, vcc
	v_mul_f32_e32 v65, v87, v64
	v_mul_f32_e32 v64, v85, v64
	v_mul_f32_e32 v67, v86, v64
	v_mul_f32_e32 v64, v81, v64
	v_mul_f32_e32 v68, v82, v64
	v_mul_f32_e32 v64, v83, v64
	v_mul_f32_e32 v66, v88, v66
	v_mul_f32_e32 v64, v84, v64
	v_cvt_pk_bf16_f32 v64, v64, v68
	v_cvt_pk_bf16_f32 v65, v67, v65
	v_cvt_pk_bf16_f32 v66, v66, v70
	v_cvt_pk_bf16_f32 v67, v90, v92
	v_cvt_pk_bf16_f32 v68, v91, v80
	v_cvt_pk_bf16_f32 v69, v75, v74
	v_cvt_pk_bf16_f32 v70, v77, v78
	v_cvt_pk_bf16_f32 v71, v76, v79
	v_mul_f32_e32 v177, v72, v73
	s_waitcnt vmcnt(12)
	s_setprio 1
	v_mfma_f32_32x32x16_bf16 v[48:63], v[158:161], v[64:67], v[48:63]
	v_cmp_gt_f32_e64 s[42:43], s1, v177
	s_or_b64 s[92:93], s[92:93], exec
	s_mov_b64 s[44:45], -1
	s_cmp_lg_u64 s[42:43], exec
	v_mfma_f32_32x32x16_bf16 v[32:47], v[150:153], v[64:67], v[32:47]
	s_waitcnt vmcnt(11)
	v_mfma_f32_32x32x16_bf16 v[16:31], v[146:149], v[64:67], v[16:31]
	s_waitcnt vmcnt(9)
	v_mfma_f32_32x32x16_bf16 v[0:15], v[134:137], v[64:67], v[0:15]
	v_mfma_f32_32x32x16_bf16 v[48:63], v[154:157], v[68:71], v[48:63]
	v_mfma_f32_32x32x16_bf16 v[32:47], v[142:145], v[68:71], v[32:47]
	v_mfma_f32_32x32x16_bf16 v[16:31], v[138:141], v[68:71], v[16:31]
	s_waitcnt vmcnt(8)
	v_mfma_f32_32x32x16_bf16 v[0:15], v[130:133], v[68:71], v[0:15]
	s_setprio 0
	s_cbranch_scc1 .LBB0_117
	s_branch .LBB0_118
